# plus prep phase: adaLN silu(c) staging loop loads batched (48 serialized loads per K-chunk -> two groups of 24)
# speedup vs baseline: 1.0037x; 1.0037x over previous
; DEV float siluf_(float x) { return x / (1.0f + __expf(-x)); }
; DEV void mod_item(const Params& p, int item, unsigned char* smem) {
;     ...
;     for (int e = tid; e < 48 * 256; e += NT) {
;       int b = e >> 8, k = e & 255;
;       float c = b < 16 ? p.c_p[b * 1024 + kc * 256 + k] : p.c_s[(b - 16) * 1024 + kc * 256 + k];
;       sc[e] = siluf_(c);
;     }
.LBB0_190:
	v_mov_b32_e32 v253, 0
	v_add_u32_e32 v252, 0x0, v25
	v_lshl_add_u64 v[250:251], v[252:253], 2, s[44:45]
	global_load_dword v208, v[250:251], off
	v_add_u32_e32 v252, 0x400, v25
	v_lshl_add_u64 v[250:251], v[252:253], 2, s[44:45]
	global_load_dword v209, v[250:251], off
	v_add_u32_e32 v252, 0x800, v25
	v_lshl_add_u64 v[250:251], v[252:253], 2, s[44:45]
	global_load_dword v210, v[250:251], off
	v_add_u32_e32 v252, 0xc00, v25
	v_lshl_add_u64 v[250:251], v[252:253], 2, s[44:45]
	global_load_dword v211, v[250:251], off
	v_add_u32_e32 v252, 0x1000, v25
	v_lshl_add_u64 v[250:251], v[252:253], 2, s[44:45]
	global_load_dword v212, v[250:251], off
	v_add_u32_e32 v252, 0x1400, v25
	v_lshl_add_u64 v[250:251], v[252:253], 2, s[44:45]
	global_load_dword v213, v[250:251], off
	v_add_u32_e32 v252, 0x1800, v25
	v_lshl_add_u64 v[250:251], v[252:253], 2, s[44:45]
	global_load_dword v214, v[250:251], off
	v_add_u32_e32 v252, 0x1c00, v25
	v_lshl_add_u64 v[250:251], v[252:253], 2, s[44:45]
	global_load_dword v215, v[250:251], off
	v_add_u32_e32 v252, 0x2000, v25
	v_lshl_add_u64 v[250:251], v[252:253], 2, s[44:45]
	global_load_dword v216, v[250:251], off
	v_add_u32_e32 v252, 0x2400, v25
	v_lshl_add_u64 v[250:251], v[252:253], 2, s[44:45]
	global_load_dword v217, v[250:251], off
	v_add_u32_e32 v252, 0x2800, v25
	v_lshl_add_u64 v[250:251], v[252:253], 2, s[44:45]
	global_load_dword v218, v[250:251], off
	v_add_u32_e32 v252, 0x2c00, v25
	v_lshl_add_u64 v[250:251], v[252:253], 2, s[44:45]
	global_load_dword v219, v[250:251], off
	v_add_u32_e32 v252, 0x3000, v25
	v_lshl_add_u64 v[250:251], v[252:253], 2, s[44:45]
	global_load_dword v220, v[250:251], off
	v_add_u32_e32 v252, 0x3400, v25
	v_lshl_add_u64 v[250:251], v[252:253], 2, s[44:45]
	global_load_dword v221, v[250:251], off
	v_add_u32_e32 v252, 0x3800, v25
	v_lshl_add_u64 v[250:251], v[252:253], 2, s[44:45]
	global_load_dword v222, v[250:251], off
	v_add_u32_e32 v252, 0x3c00, v25
	v_lshl_add_u64 v[250:251], v[252:253], 2, s[44:45]
	global_load_dword v223, v[250:251], off
	v_add_u32_e32 v252, 0x4000, v24
	v_lshl_add_u64 v[250:251], v[252:253], 2, s[46:47]
	global_load_dword v224, v[250:251], off
	v_add_u32_e32 v252, 0x4400, v24
	v_lshl_add_u64 v[250:251], v[252:253], 2, s[46:47]
	global_load_dword v225, v[250:251], off
	v_add_u32_e32 v252, 0x4800, v24
	v_lshl_add_u64 v[250:251], v[252:253], 2, s[46:47]
	global_load_dword v226, v[250:251], off
	v_add_u32_e32 v252, 0x4c00, v24
	v_lshl_add_u64 v[250:251], v[252:253], 2, s[46:47]
	global_load_dword v227, v[250:251], off
	v_add_u32_e32 v252, 0x5000, v24
	v_lshl_add_u64 v[250:251], v[252:253], 2, s[46:47]
	global_load_dword v228, v[250:251], off
	v_add_u32_e32 v252, 0x5400, v24
	v_lshl_add_u64 v[250:251], v[252:253], 2, s[46:47]
	global_load_dword v229, v[250:251], off
	v_add_u32_e32 v252, 0x5800, v24
	v_lshl_add_u64 v[250:251], v[252:253], 2, s[46:47]
	global_load_dword v230, v[250:251], off
	v_add_u32_e32 v252, 0x5c00, v24
	v_lshl_add_u64 v[250:251], v[252:253], 2, s[46:47]
	global_load_dword v231, v[250:251], off
	s_waitcnt vmcnt(23)
	v_mul_f32_e32 v240, 0xbfb8aa3b, v208
	v_exp_f32_e32 v240, v240
	s_nop 0
	v_add_f32_e32 v240, 1.0, v240
	v_div_scale_f32 v241, s[18:19], v240, v240, v208
	v_rcp_f32_e32 v242, v241
	v_div_scale_f32 v243, vcc, v208, v240, v208
	v_fma_f32 v244, -v241, v242, 1.0
	v_fmac_f32_e32 v242, v244, v242
	v_mul_f32_e32 v244, v243, v242
	v_fma_f32 v245, -v241, v244, v243
	v_fmac_f32_e32 v244, v245, v242
	v_fma_f32 v241, -v241, v244, v243
	v_div_fmas_f32 v241, v241, v242, v244
	v_div_fixup_f32 v208, v241, v240, v208
	ds_write_b32 v28, v208
	s_waitcnt vmcnt(22)
	v_mul_f32_e32 v240, 0xbfb8aa3b, v209
	v_exp_f32_e32 v240, v240
	s_nop 0
	v_add_f32_e32 v240, 1.0, v240
	v_div_scale_f32 v241, s[18:19], v240, v240, v209
	v_rcp_f32_e32 v242, v241
	v_div_scale_f32 v243, vcc, v209, v240, v209
	v_fma_f32 v244, -v241, v242, 1.0
	v_fmac_f32_e32 v242, v244, v242
	v_mul_f32_e32 v244, v243, v242
	v_fma_f32 v245, -v241, v244, v243
	v_fmac_f32_e32 v244, v245, v242
	v_fma_f32 v241, -v241, v244, v243
	v_div_fmas_f32 v241, v241, v242, v244
	v_div_fixup_f32 v209, v241, v240, v209
	ds_write_b32 v28, v209 offset:1024
	s_waitcnt vmcnt(21)
	v_mul_f32_e32 v240, 0xbfb8aa3b, v210
	v_exp_f32_e32 v240, v240
	s_nop 0
	v_add_f32_e32 v240, 1.0, v240
	v_div_scale_f32 v241, s[18:19], v240, v240, v210
	v_rcp_f32_e32 v242, v241
	v_div_scale_f32 v243, vcc, v210, v240, v210
	v_fma_f32 v244, -v241, v242, 1.0
	v_fmac_f32_e32 v242, v244, v242
	v_mul_f32_e32 v244, v243, v242
	v_fma_f32 v245, -v241, v244, v243
	v_fmac_f32_e32 v244, v245, v242
	v_fma_f32 v241, -v241, v244, v243
	v_div_fmas_f32 v241, v241, v242, v244
	v_div_fixup_f32 v210, v241, v240, v210
	ds_write_b32 v28, v210 offset:2048
	s_waitcnt vmcnt(20)
	v_mul_f32_e32 v240, 0xbfb8aa3b, v211
	v_exp_f32_e32 v240, v240
	s_nop 0
	v_add_f32_e32 v240, 1.0, v240
	v_div_scale_f32 v241, s[18:19], v240, v240, v211
	v_rcp_f32_e32 v242, v241
	v_div_scale_f32 v243, vcc, v211, v240, v211
	v_fma_f32 v244, -v241, v242, 1.0
	v_fmac_f32_e32 v242, v244, v242
	v_mul_f32_e32 v244, v243, v242
	v_fma_f32 v245, -v241, v244, v243
	v_fmac_f32_e32 v244, v245, v242
	v_fma_f32 v241, -v241, v244, v243
	v_div_fmas_f32 v241, v241, v242, v244
	v_div_fixup_f32 v211, v241, v240, v211
	ds_write_b32 v28, v211 offset:3072
	s_waitcnt vmcnt(19)
	v_mul_f32_e32 v240, 0xbfb8aa3b, v212
	v_exp_f32_e32 v240, v240
	s_nop 0
	v_add_f32_e32 v240, 1.0, v240
	v_div_scale_f32 v241, s[18:19], v240, v240, v212
	v_rcp_f32_e32 v242, v241
	v_div_scale_f32 v243, vcc, v212, v240, v212
	v_fma_f32 v244, -v241, v242, 1.0
	v_fmac_f32_e32 v242, v244, v242
	v_mul_f32_e32 v244, v243, v242
	v_fma_f32 v245, -v241, v244, v243
	v_fmac_f32_e32 v244, v245, v242
	v_fma_f32 v241, -v241, v244, v243
	v_div_fmas_f32 v241, v241, v242, v244
	v_div_fixup_f32 v212, v241, v240, v212
	ds_write_b32 v28, v212 offset:4096
	s_waitcnt vmcnt(18)
; DEV float siluf_(float x) { return x / (1.0f + __expf(-x)); }
; DEV void mod_item(const Params& p, int item, unsigned char* smem) {
;     ...
;     for (int e = tid; e < 48 * 256; e += NT) {
;       int b = e >> 8, k = e & 255;
;       float c = b < 16 ? p.c_p[b * 1024 + kc * 256 + k] : p.c_s[(b - 16) * 1024 + kc * 256 + k];
;       sc[e] = siluf_(c);
;     }
	v_mul_f32_e32 v240, 0xbfb8aa3b, v213
	v_exp_f32_e32 v240, v240
	s_nop 0
	v_add_f32_e32 v240, 1.0, v240
	v_div_scale_f32 v241, s[18:19], v240, v240, v213
	v_rcp_f32_e32 v242, v241
	v_div_scale_f32 v243, vcc, v213, v240, v213
	v_fma_f32 v244, -v241, v242, 1.0
	v_fmac_f32_e32 v242, v244, v242
	v_mul_f32_e32 v244, v243, v242
	v_fma_f32 v245, -v241, v244, v243
	v_fmac_f32_e32 v244, v245, v242
	v_fma_f32 v241, -v241, v244, v243
	v_div_fmas_f32 v241, v241, v242, v244
	v_div_fixup_f32 v213, v241, v240, v213
	ds_write_b32 v28, v213 offset:5120
	s_waitcnt vmcnt(17)
	v_mul_f32_e32 v240, 0xbfb8aa3b, v214
	v_exp_f32_e32 v240, v240
	s_nop 0
	v_add_f32_e32 v240, 1.0, v240
	v_div_scale_f32 v241, s[18:19], v240, v240, v214
	v_rcp_f32_e32 v242, v241
	v_div_scale_f32 v243, vcc, v214, v240, v214
	v_fma_f32 v244, -v241, v242, 1.0
	v_fmac_f32_e32 v242, v244, v242
	v_mul_f32_e32 v244, v243, v242
	v_fma_f32 v245, -v241, v244, v243
	v_fmac_f32_e32 v244, v245, v242
	v_fma_f32 v241, -v241, v244, v243
	v_div_fmas_f32 v241, v241, v242, v244
	v_div_fixup_f32 v214, v241, v240, v214
	ds_write_b32 v28, v214 offset:6144
	s_waitcnt vmcnt(16)
	v_mul_f32_e32 v240, 0xbfb8aa3b, v215
	v_exp_f32_e32 v240, v240
	s_nop 0
	v_add_f32_e32 v240, 1.0, v240
	v_div_scale_f32 v241, s[18:19], v240, v240, v215
	v_rcp_f32_e32 v242, v241
	v_div_scale_f32 v243, vcc, v215, v240, v215
	v_fma_f32 v244, -v241, v242, 1.0
	v_fmac_f32_e32 v242, v244, v242
	v_mul_f32_e32 v244, v243, v242
	v_fma_f32 v245, -v241, v244, v243
	v_fmac_f32_e32 v244, v245, v242
	v_fma_f32 v241, -v241, v244, v243
	v_div_fmas_f32 v241, v241, v242, v244
	v_div_fixup_f32 v215, v241, v240, v215
	ds_write_b32 v28, v215 offset:7168
	s_waitcnt vmcnt(15)
	v_mul_f32_e32 v240, 0xbfb8aa3b, v216
	v_exp_f32_e32 v240, v240
	s_nop 0
	v_add_f32_e32 v240, 1.0, v240
	v_div_scale_f32 v241, s[18:19], v240, v240, v216
	v_rcp_f32_e32 v242, v241
	v_div_scale_f32 v243, vcc, v216, v240, v216
	v_fma_f32 v244, -v241, v242, 1.0
	v_fmac_f32_e32 v242, v244, v242
	v_mul_f32_e32 v244, v243, v242
	v_fma_f32 v245, -v241, v244, v243
	v_fmac_f32_e32 v244, v245, v242
	v_fma_f32 v241, -v241, v244, v243
	v_div_fmas_f32 v241, v241, v242, v244
	v_div_fixup_f32 v216, v241, v240, v216
	ds_write_b32 v28, v216 offset:8192
	s_waitcnt vmcnt(14)
	v_mul_f32_e32 v240, 0xbfb8aa3b, v217
	v_exp_f32_e32 v240, v240
	s_nop 0
	v_add_f32_e32 v240, 1.0, v240
	v_div_scale_f32 v241, s[18:19], v240, v240, v217
	v_rcp_f32_e32 v242, v241
	v_div_scale_f32 v243, vcc, v217, v240, v217
	v_fma_f32 v244, -v241, v242, 1.0
	v_fmac_f32_e32 v242, v244, v242
	v_mul_f32_e32 v244, v243, v242
	v_fma_f32 v245, -v241, v244, v243
	v_fmac_f32_e32 v244, v245, v242
	v_fma_f32 v241, -v241, v244, v243
	v_div_fmas_f32 v241, v241, v242, v244
	v_div_fixup_f32 v217, v241, v240, v217
	ds_write_b32 v28, v217 offset:9216
	s_waitcnt vmcnt(13)
	v_mul_f32_e32 v240, 0xbfb8aa3b, v218
	v_exp_f32_e32 v240, v240
	s_nop 0
	v_add_f32_e32 v240, 1.0, v240
	v_div_scale_f32 v241, s[18:19], v240, v240, v218
	v_rcp_f32_e32 v242, v241
	v_div_scale_f32 v243, vcc, v218, v240, v218
	v_fma_f32 v244, -v241, v242, 1.0
	v_fmac_f32_e32 v242, v244, v242
	v_mul_f32_e32 v244, v243, v242
	v_fma_f32 v245, -v241, v244, v243
	v_fmac_f32_e32 v244, v245, v242
	v_fma_f32 v241, -v241, v244, v243
	v_div_fmas_f32 v241, v241, v242, v244
	v_div_fixup_f32 v218, v241, v240, v218
	ds_write_b32 v28, v218 offset:10240
	s_waitcnt vmcnt(12)
	v_mul_f32_e32 v240, 0xbfb8aa3b, v219
	v_exp_f32_e32 v240, v240
	s_nop 0
	v_add_f32_e32 v240, 1.0, v240
	v_div_scale_f32 v241, s[18:19], v240, v240, v219
	v_rcp_f32_e32 v242, v241
	v_div_scale_f32 v243, vcc, v219, v240, v219
	v_fma_f32 v244, -v241, v242, 1.0
	v_fmac_f32_e32 v242, v244, v242
	v_mul_f32_e32 v244, v243, v242
	v_fma_f32 v245, -v241, v244, v243
	v_fmac_f32_e32 v244, v245, v242
	v_fma_f32 v241, -v241, v244, v243
	v_div_fmas_f32 v241, v241, v242, v244
	v_div_fixup_f32 v219, v241, v240, v219
	ds_write_b32 v28, v219 offset:11264
	s_waitcnt vmcnt(11)
	v_mul_f32_e32 v240, 0xbfb8aa3b, v220
	v_exp_f32_e32 v240, v240
	s_nop 0
	v_add_f32_e32 v240, 1.0, v240
	v_div_scale_f32 v241, s[18:19], v240, v240, v220
	v_rcp_f32_e32 v242, v241
	v_div_scale_f32 v243, vcc, v220, v240, v220
	v_fma_f32 v244, -v241, v242, 1.0
	v_fmac_f32_e32 v242, v244, v242
	v_mul_f32_e32 v244, v243, v242
	v_fma_f32 v245, -v241, v244, v243
	v_fmac_f32_e32 v244, v245, v242
	v_fma_f32 v241, -v241, v244, v243
	v_div_fmas_f32 v241, v241, v242, v244
	v_div_fixup_f32 v220, v241, v240, v220
	ds_write_b32 v28, v220 offset:12288
	s_waitcnt vmcnt(10)
	v_mul_f32_e32 v240, 0xbfb8aa3b, v221
	v_exp_f32_e32 v240, v240
	s_nop 0
	v_add_f32_e32 v240, 1.0, v240
	v_div_scale_f32 v241, s[18:19], v240, v240, v221
	v_rcp_f32_e32 v242, v241
	v_div_scale_f32 v243, vcc, v221, v240, v221
	v_fma_f32 v244, -v241, v242, 1.0
	v_fmac_f32_e32 v242, v244, v242
	v_mul_f32_e32 v244, v243, v242
	v_fma_f32 v245, -v241, v244, v243
	v_fmac_f32_e32 v244, v245, v242
	v_fma_f32 v241, -v241, v244, v243
	v_div_fmas_f32 v241, v241, v242, v244
	v_div_fixup_f32 v221, v241, v240, v221
	ds_write_b32 v28, v221 offset:13312
	s_waitcnt vmcnt(9)
	v_mul_f32_e32 v240, 0xbfb8aa3b, v222
	v_exp_f32_e32 v240, v240
	s_nop 0
	v_add_f32_e32 v240, 1.0, v240
	v_div_scale_f32 v241, s[18:19], v240, v240, v222
	v_rcp_f32_e32 v242, v241
	v_div_scale_f32 v243, vcc, v222, v240, v222
	v_fma_f32 v244, -v241, v242, 1.0
	v_fmac_f32_e32 v242, v244, v242
	v_mul_f32_e32 v244, v243, v242
	v_fma_f32 v245, -v241, v244, v243
	v_fmac_f32_e32 v244, v245, v242
	v_fma_f32 v241, -v241, v244, v243
	v_div_fmas_f32 v241, v241, v242, v244
	v_div_fixup_f32 v222, v241, v240, v222
	ds_write_b32 v28, v222 offset:14336
	s_waitcnt vmcnt(8)
; DEV float siluf_(float x) { return x / (1.0f + __expf(-x)); }
; DEV void mod_item(const Params& p, int item, unsigned char* smem) {
;     ...
;     for (int e = tid; e < 48 * 256; e += NT) {
;       int b = e >> 8, k = e & 255;
;       float c = b < 16 ? p.c_p[b * 1024 + kc * 256 + k] : p.c_s[(b - 16) * 1024 + kc * 256 + k];
;       sc[e] = siluf_(c);
;     }
	v_mul_f32_e32 v240, 0xbfb8aa3b, v223
	v_exp_f32_e32 v240, v240
	s_nop 0
	v_add_f32_e32 v240, 1.0, v240
	v_div_scale_f32 v241, s[18:19], v240, v240, v223
	v_rcp_f32_e32 v242, v241
	v_div_scale_f32 v243, vcc, v223, v240, v223
	v_fma_f32 v244, -v241, v242, 1.0
	v_fmac_f32_e32 v242, v244, v242
	v_mul_f32_e32 v244, v243, v242
	v_fma_f32 v245, -v241, v244, v243
	v_fmac_f32_e32 v244, v245, v242
	v_fma_f32 v241, -v241, v244, v243
	v_div_fmas_f32 v241, v241, v242, v244
	v_div_fixup_f32 v223, v241, v240, v223
	ds_write_b32 v28, v223 offset:15360
	s_waitcnt vmcnt(7)
	v_mul_f32_e32 v240, 0xbfb8aa3b, v224
	v_exp_f32_e32 v240, v240
	s_nop 0
	v_add_f32_e32 v240, 1.0, v240
	v_div_scale_f32 v241, s[18:19], v240, v240, v224
	v_rcp_f32_e32 v242, v241
	v_div_scale_f32 v243, vcc, v224, v240, v224
	v_fma_f32 v244, -v241, v242, 1.0
	v_fmac_f32_e32 v242, v244, v242
	v_mul_f32_e32 v244, v243, v242
	v_fma_f32 v245, -v241, v244, v243
	v_fmac_f32_e32 v244, v245, v242
	v_fma_f32 v241, -v241, v244, v243
	v_div_fmas_f32 v241, v241, v242, v244
	v_div_fixup_f32 v224, v241, v240, v224
	ds_write_b32 v28, v224 offset:16384
	s_waitcnt vmcnt(6)
	v_mul_f32_e32 v240, 0xbfb8aa3b, v225
	v_exp_f32_e32 v240, v240
	s_nop 0
	v_add_f32_e32 v240, 1.0, v240
	v_div_scale_f32 v241, s[18:19], v240, v240, v225
	v_rcp_f32_e32 v242, v241
	v_div_scale_f32 v243, vcc, v225, v240, v225
	v_fma_f32 v244, -v241, v242, 1.0
	v_fmac_f32_e32 v242, v244, v242
	v_mul_f32_e32 v244, v243, v242
	v_fma_f32 v245, -v241, v244, v243
	v_fmac_f32_e32 v244, v245, v242
	v_fma_f32 v241, -v241, v244, v243
	v_div_fmas_f32 v241, v241, v242, v244
	v_div_fixup_f32 v225, v241, v240, v225
	ds_write_b32 v28, v225 offset:17408
	s_waitcnt vmcnt(5)
	v_mul_f32_e32 v240, 0xbfb8aa3b, v226
	v_exp_f32_e32 v240, v240
	s_nop 0
	v_add_f32_e32 v240, 1.0, v240
	v_div_scale_f32 v241, s[18:19], v240, v240, v226
	v_rcp_f32_e32 v242, v241
	v_div_scale_f32 v243, vcc, v226, v240, v226
	v_fma_f32 v244, -v241, v242, 1.0
	v_fmac_f32_e32 v242, v244, v242
	v_mul_f32_e32 v244, v243, v242
	v_fma_f32 v245, -v241, v244, v243
	v_fmac_f32_e32 v244, v245, v242
	v_fma_f32 v241, -v241, v244, v243
	v_div_fmas_f32 v241, v241, v242, v244
	v_div_fixup_f32 v226, v241, v240, v226
	ds_write_b32 v28, v226 offset:18432
	s_waitcnt vmcnt(4)
	v_mul_f32_e32 v240, 0xbfb8aa3b, v227
	v_exp_f32_e32 v240, v240
	s_nop 0
	v_add_f32_e32 v240, 1.0, v240
	v_div_scale_f32 v241, s[18:19], v240, v240, v227
	v_rcp_f32_e32 v242, v241
	v_div_scale_f32 v243, vcc, v227, v240, v227
	v_fma_f32 v244, -v241, v242, 1.0
	v_fmac_f32_e32 v242, v244, v242
	v_mul_f32_e32 v244, v243, v242
	v_fma_f32 v245, -v241, v244, v243
	v_fmac_f32_e32 v244, v245, v242
	v_fma_f32 v241, -v241, v244, v243
	v_div_fmas_f32 v241, v241, v242, v244
	v_div_fixup_f32 v227, v241, v240, v227
	ds_write_b32 v28, v227 offset:19456
	s_waitcnt vmcnt(3)
	v_mul_f32_e32 v240, 0xbfb8aa3b, v228
	v_exp_f32_e32 v240, v240
	s_nop 0
	v_add_f32_e32 v240, 1.0, v240
	v_div_scale_f32 v241, s[18:19], v240, v240, v228
	v_rcp_f32_e32 v242, v241
	v_div_scale_f32 v243, vcc, v228, v240, v228
	v_fma_f32 v244, -v241, v242, 1.0
	v_fmac_f32_e32 v242, v244, v242
	v_mul_f32_e32 v244, v243, v242
	v_fma_f32 v245, -v241, v244, v243
	v_fmac_f32_e32 v244, v245, v242
	v_fma_f32 v241, -v241, v244, v243
	v_div_fmas_f32 v241, v241, v242, v244
	v_div_fixup_f32 v228, v241, v240, v228
	ds_write_b32 v28, v228 offset:20480
	s_waitcnt vmcnt(2)
	v_mul_f32_e32 v240, 0xbfb8aa3b, v229
	v_exp_f32_e32 v240, v240
	s_nop 0
	v_add_f32_e32 v240, 1.0, v240
	v_div_scale_f32 v241, s[18:19], v240, v240, v229
	v_rcp_f32_e32 v242, v241
	v_div_scale_f32 v243, vcc, v229, v240, v229
	v_fma_f32 v244, -v241, v242, 1.0
	v_fmac_f32_e32 v242, v244, v242
	v_mul_f32_e32 v244, v243, v242
	v_fma_f32 v245, -v241, v244, v243
	v_fmac_f32_e32 v244, v245, v242
	v_fma_f32 v241, -v241, v244, v243
	v_div_fmas_f32 v241, v241, v242, v244
	v_div_fixup_f32 v229, v241, v240, v229
	ds_write_b32 v28, v229 offset:21504
	s_waitcnt vmcnt(1)
	v_mul_f32_e32 v240, 0xbfb8aa3b, v230
	v_exp_f32_e32 v240, v240
	s_nop 0
	v_add_f32_e32 v240, 1.0, v240
	v_div_scale_f32 v241, s[18:19], v240, v240, v230
	v_rcp_f32_e32 v242, v241
	v_div_scale_f32 v243, vcc, v230, v240, v230
	v_fma_f32 v244, -v241, v242, 1.0
	v_fmac_f32_e32 v242, v244, v242
	v_mul_f32_e32 v244, v243, v242
	v_fma_f32 v245, -v241, v244, v243
	v_fmac_f32_e32 v244, v245, v242
	v_fma_f32 v241, -v241, v244, v243
	v_div_fmas_f32 v241, v241, v242, v244
	v_div_fixup_f32 v230, v241, v240, v230
	ds_write_b32 v28, v230 offset:22528
	s_waitcnt vmcnt(0)
; DEV float siluf_(float x) { return x / (1.0f + __expf(-x)); }
; DEV void mod_item(const Params& p, int item, unsigned char* smem) {
;     ...
;     for (int e = tid; e < 48 * 256; e += NT) {
;       int b = e >> 8, k = e & 255;
;       float c = b < 16 ? p.c_p[b * 1024 + kc * 256 + k] : p.c_s[(b - 16) * 1024 + kc * 256 + k];
;       sc[e] = siluf_(c);
;     }
	v_mul_f32_e32 v240, 0xbfb8aa3b, v231
	v_exp_f32_e32 v240, v240
	s_nop 0
	v_add_f32_e32 v240, 1.0, v240
	v_div_scale_f32 v241, s[18:19], v240, v240, v231
	v_rcp_f32_e32 v242, v241
	v_div_scale_f32 v243, vcc, v231, v240, v231
	v_fma_f32 v244, -v241, v242, 1.0
	v_fmac_f32_e32 v242, v244, v242
	v_mul_f32_e32 v244, v243, v242
	v_fma_f32 v245, -v241, v244, v243
	v_fmac_f32_e32 v244, v245, v242
	v_fma_f32 v241, -v241, v244, v243
	v_div_fmas_f32 v241, v241, v242, v244
	v_div_fixup_f32 v231, v241, v240, v231
	ds_write_b32 v28, v231 offset:23552
	v_add_u32_e32 v252, 0x6000, v24
	v_lshl_add_u64 v[250:251], v[252:253], 2, s[46:47]
	global_load_dword v208, v[250:251], off
	v_add_u32_e32 v252, 0x6400, v24
	v_lshl_add_u64 v[250:251], v[252:253], 2, s[46:47]
	global_load_dword v209, v[250:251], off
	v_add_u32_e32 v252, 0x6800, v24
	v_lshl_add_u64 v[250:251], v[252:253], 2, s[46:47]
	global_load_dword v210, v[250:251], off
	v_add_u32_e32 v252, 0x6c00, v24
	v_lshl_add_u64 v[250:251], v[252:253], 2, s[46:47]
	global_load_dword v211, v[250:251], off
	v_add_u32_e32 v252, 0x7000, v24
	v_lshl_add_u64 v[250:251], v[252:253], 2, s[46:47]
	global_load_dword v212, v[250:251], off
	v_add_u32_e32 v252, 0x7400, v24
	v_lshl_add_u64 v[250:251], v[252:253], 2, s[46:47]
	global_load_dword v213, v[250:251], off
	v_add_u32_e32 v252, 0x7800, v24
	v_lshl_add_u64 v[250:251], v[252:253], 2, s[46:47]
	global_load_dword v214, v[250:251], off
	v_add_u32_e32 v252, 0x7c00, v24
	v_lshl_add_u64 v[250:251], v[252:253], 2, s[46:47]
	global_load_dword v215, v[250:251], off
	v_add_u32_e32 v252, 0x8000, v24
	v_lshl_add_u64 v[250:251], v[252:253], 2, s[46:47]
	global_load_dword v216, v[250:251], off
	v_add_u32_e32 v252, 0x8400, v24
	v_lshl_add_u64 v[250:251], v[252:253], 2, s[46:47]
	global_load_dword v217, v[250:251], off
	v_add_u32_e32 v252, 0x8800, v24
	v_lshl_add_u64 v[250:251], v[252:253], 2, s[46:47]
	global_load_dword v218, v[250:251], off
	v_add_u32_e32 v252, 0x8c00, v24
	v_lshl_add_u64 v[250:251], v[252:253], 2, s[46:47]
	global_load_dword v219, v[250:251], off
	v_add_u32_e32 v252, 0x9000, v24
	v_lshl_add_u64 v[250:251], v[252:253], 2, s[46:47]
	global_load_dword v220, v[250:251], off
	v_add_u32_e32 v252, 0x9400, v24
	v_lshl_add_u64 v[250:251], v[252:253], 2, s[46:47]
	global_load_dword v221, v[250:251], off
	v_add_u32_e32 v252, 0x9800, v24
	v_lshl_add_u64 v[250:251], v[252:253], 2, s[46:47]
	global_load_dword v222, v[250:251], off
	v_add_u32_e32 v252, 0x9c00, v24
	v_lshl_add_u64 v[250:251], v[252:253], 2, s[46:47]
	global_load_dword v223, v[250:251], off
	v_add_u32_e32 v252, 0xa000, v24
	v_lshl_add_u64 v[250:251], v[252:253], 2, s[46:47]
	global_load_dword v224, v[250:251], off
	v_add_u32_e32 v252, 0xa400, v24
	v_lshl_add_u64 v[250:251], v[252:253], 2, s[46:47]
	global_load_dword v225, v[250:251], off
	v_add_u32_e32 v252, 0xa800, v24
	v_lshl_add_u64 v[250:251], v[252:253], 2, s[46:47]
	global_load_dword v226, v[250:251], off
	v_add_u32_e32 v252, 0xac00, v24
	v_lshl_add_u64 v[250:251], v[252:253], 2, s[46:47]
	global_load_dword v227, v[250:251], off
	v_add_u32_e32 v252, 0xb000, v24
	v_lshl_add_u64 v[250:251], v[252:253], 2, s[46:47]
	global_load_dword v228, v[250:251], off
	v_add_u32_e32 v252, 0xb400, v24
	v_lshl_add_u64 v[250:251], v[252:253], 2, s[46:47]
	global_load_dword v229, v[250:251], off
	v_add_u32_e32 v252, 0xb800, v24
	v_lshl_add_u64 v[250:251], v[252:253], 2, s[46:47]
	global_load_dword v230, v[250:251], off
	v_add_u32_e32 v252, 0xbc00, v24
	v_lshl_add_u64 v[250:251], v[252:253], 2, s[46:47]
	global_load_dword v231, v[250:251], off
	s_waitcnt vmcnt(23)
	v_mul_f32_e32 v240, 0xbfb8aa3b, v208
	v_exp_f32_e32 v240, v240
	s_nop 0
	v_add_f32_e32 v240, 1.0, v240
	v_div_scale_f32 v241, s[18:19], v240, v240, v208
	v_rcp_f32_e32 v242, v241
	v_div_scale_f32 v243, vcc, v208, v240, v208
	v_fma_f32 v244, -v241, v242, 1.0
	v_fmac_f32_e32 v242, v244, v242
	v_mul_f32_e32 v244, v243, v242
	v_fma_f32 v245, -v241, v244, v243
	v_fmac_f32_e32 v244, v245, v242
	v_fma_f32 v241, -v241, v244, v243
	v_div_fmas_f32 v241, v241, v242, v244
	v_div_fixup_f32 v208, v241, v240, v208
	ds_write_b32 v28, v208 offset:24576
	s_waitcnt vmcnt(22)
	v_mul_f32_e32 v240, 0xbfb8aa3b, v209
	v_exp_f32_e32 v240, v240
	s_nop 0
	v_add_f32_e32 v240, 1.0, v240
	v_div_scale_f32 v241, s[18:19], v240, v240, v209
	v_rcp_f32_e32 v242, v241
	v_div_scale_f32 v243, vcc, v209, v240, v209
	v_fma_f32 v244, -v241, v242, 1.0
	v_fmac_f32_e32 v242, v244, v242
	v_mul_f32_e32 v244, v243, v242
	v_fma_f32 v245, -v241, v244, v243
	v_fmac_f32_e32 v244, v245, v242
	v_fma_f32 v241, -v241, v244, v243
	v_div_fmas_f32 v241, v241, v242, v244
	v_div_fixup_f32 v209, v241, v240, v209
	ds_write_b32 v28, v209 offset:25600
	s_waitcnt vmcnt(21)
	v_mul_f32_e32 v240, 0xbfb8aa3b, v210
	v_exp_f32_e32 v240, v240
	s_nop 0
	v_add_f32_e32 v240, 1.0, v240
	v_div_scale_f32 v241, s[18:19], v240, v240, v210
	v_rcp_f32_e32 v242, v241
	v_div_scale_f32 v243, vcc, v210, v240, v210
	v_fma_f32 v244, -v241, v242, 1.0
	v_fmac_f32_e32 v242, v244, v242
	v_mul_f32_e32 v244, v243, v242
	v_fma_f32 v245, -v241, v244, v243
	v_fmac_f32_e32 v244, v245, v242
	v_fma_f32 v241, -v241, v244, v243
	v_div_fmas_f32 v241, v241, v242, v244
	v_div_fixup_f32 v210, v241, v240, v210
	ds_write_b32 v28, v210 offset:26624
	s_waitcnt vmcnt(20)
	v_mul_f32_e32 v240, 0xbfb8aa3b, v211
	v_exp_f32_e32 v240, v240
	s_nop 0
	v_add_f32_e32 v240, 1.0, v240
	v_div_scale_f32 v241, s[18:19], v240, v240, v211
	v_rcp_f32_e32 v242, v241
	v_div_scale_f32 v243, vcc, v211, v240, v211
	v_fma_f32 v244, -v241, v242, 1.0
	v_fmac_f32_e32 v242, v244, v242
	v_mul_f32_e32 v244, v243, v242
	v_fma_f32 v245, -v241, v244, v243
	v_fmac_f32_e32 v244, v245, v242
	v_fma_f32 v241, -v241, v244, v243
	v_div_fmas_f32 v241, v241, v242, v244
	v_div_fixup_f32 v211, v241, v240, v211
	ds_write_b32 v28, v211 offset:27648
	s_waitcnt vmcnt(19)
; DEV float siluf_(float x) { return x / (1.0f + __expf(-x)); }
; DEV void mod_item(const Params& p, int item, unsigned char* smem) {
;     ...
;     for (int e = tid; e < 48 * 256; e += NT) {
;       int b = e >> 8, k = e & 255;
;       float c = b < 16 ? p.c_p[b * 1024 + kc * 256 + k] : p.c_s[(b - 16) * 1024 + kc * 256 + k];
;       sc[e] = siluf_(c);
;     }
	v_mul_f32_e32 v240, 0xbfb8aa3b, v212
	v_exp_f32_e32 v240, v240
	s_nop 0
	v_add_f32_e32 v240, 1.0, v240
	v_div_scale_f32 v241, s[18:19], v240, v240, v212
	v_rcp_f32_e32 v242, v241
	v_div_scale_f32 v243, vcc, v212, v240, v212
	v_fma_f32 v244, -v241, v242, 1.0
	v_fmac_f32_e32 v242, v244, v242
	v_mul_f32_e32 v244, v243, v242
	v_fma_f32 v245, -v241, v244, v243
	v_fmac_f32_e32 v244, v245, v242
	v_fma_f32 v241, -v241, v244, v243
	v_div_fmas_f32 v241, v241, v242, v244
	v_div_fixup_f32 v212, v241, v240, v212
	ds_write_b32 v28, v212 offset:28672
	s_waitcnt vmcnt(18)
	v_mul_f32_e32 v240, 0xbfb8aa3b, v213
	v_exp_f32_e32 v240, v240
	s_nop 0
	v_add_f32_e32 v240, 1.0, v240
	v_div_scale_f32 v241, s[18:19], v240, v240, v213
	v_rcp_f32_e32 v242, v241
	v_div_scale_f32 v243, vcc, v213, v240, v213
	v_fma_f32 v244, -v241, v242, 1.0
	v_fmac_f32_e32 v242, v244, v242
	v_mul_f32_e32 v244, v243, v242
	v_fma_f32 v245, -v241, v244, v243
	v_fmac_f32_e32 v244, v245, v242
	v_fma_f32 v241, -v241, v244, v243
	v_div_fmas_f32 v241, v241, v242, v244
	v_div_fixup_f32 v213, v241, v240, v213
	ds_write_b32 v28, v213 offset:29696
	s_waitcnt vmcnt(17)
	v_mul_f32_e32 v240, 0xbfb8aa3b, v214
	v_exp_f32_e32 v240, v240
	s_nop 0
	v_add_f32_e32 v240, 1.0, v240
	v_div_scale_f32 v241, s[18:19], v240, v240, v214
	v_rcp_f32_e32 v242, v241
	v_div_scale_f32 v243, vcc, v214, v240, v214
	v_fma_f32 v244, -v241, v242, 1.0
	v_fmac_f32_e32 v242, v244, v242
	v_mul_f32_e32 v244, v243, v242
	v_fma_f32 v245, -v241, v244, v243
	v_fmac_f32_e32 v244, v245, v242
	v_fma_f32 v241, -v241, v244, v243
	v_div_fmas_f32 v241, v241, v242, v244
	v_div_fixup_f32 v214, v241, v240, v214
	ds_write_b32 v28, v214 offset:30720
	s_waitcnt vmcnt(16)
	v_mul_f32_e32 v240, 0xbfb8aa3b, v215
	v_exp_f32_e32 v240, v240
	s_nop 0
	v_add_f32_e32 v240, 1.0, v240
	v_div_scale_f32 v241, s[18:19], v240, v240, v215
	v_rcp_f32_e32 v242, v241
	v_div_scale_f32 v243, vcc, v215, v240, v215
	v_fma_f32 v244, -v241, v242, 1.0
	v_fmac_f32_e32 v242, v244, v242
	v_mul_f32_e32 v244, v243, v242
	v_fma_f32 v245, -v241, v244, v243
	v_fmac_f32_e32 v244, v245, v242
	v_fma_f32 v241, -v241, v244, v243
	v_div_fmas_f32 v241, v241, v242, v244
	v_div_fixup_f32 v215, v241, v240, v215
	ds_write_b32 v28, v215 offset:31744
	s_waitcnt vmcnt(15)
	v_mul_f32_e32 v240, 0xbfb8aa3b, v216
	v_exp_f32_e32 v240, v240
	s_nop 0
	v_add_f32_e32 v240, 1.0, v240
	v_div_scale_f32 v241, s[18:19], v240, v240, v216
	v_rcp_f32_e32 v242, v241
	v_div_scale_f32 v243, vcc, v216, v240, v216
	v_fma_f32 v244, -v241, v242, 1.0
	v_fmac_f32_e32 v242, v244, v242
	v_mul_f32_e32 v244, v243, v242
	v_fma_f32 v245, -v241, v244, v243
	v_fmac_f32_e32 v244, v245, v242
	v_fma_f32 v241, -v241, v244, v243
	v_div_fmas_f32 v241, v241, v242, v244
	v_div_fixup_f32 v216, v241, v240, v216
	ds_write_b32 v28, v216 offset:32768
	s_waitcnt vmcnt(14)
	v_mul_f32_e32 v240, 0xbfb8aa3b, v217
	v_exp_f32_e32 v240, v240
	s_nop 0
	v_add_f32_e32 v240, 1.0, v240
	v_div_scale_f32 v241, s[18:19], v240, v240, v217
	v_rcp_f32_e32 v242, v241
	v_div_scale_f32 v243, vcc, v217, v240, v217
	v_fma_f32 v244, -v241, v242, 1.0
	v_fmac_f32_e32 v242, v244, v242
	v_mul_f32_e32 v244, v243, v242
	v_fma_f32 v245, -v241, v244, v243
	v_fmac_f32_e32 v244, v245, v242
	v_fma_f32 v241, -v241, v244, v243
	v_div_fmas_f32 v241, v241, v242, v244
	v_div_fixup_f32 v217, v241, v240, v217
	ds_write_b32 v28, v217 offset:33792
	s_waitcnt vmcnt(13)
	v_mul_f32_e32 v240, 0xbfb8aa3b, v218
	v_exp_f32_e32 v240, v240
	s_nop 0
	v_add_f32_e32 v240, 1.0, v240
	v_div_scale_f32 v241, s[18:19], v240, v240, v218
	v_rcp_f32_e32 v242, v241
	v_div_scale_f32 v243, vcc, v218, v240, v218
	v_fma_f32 v244, -v241, v242, 1.0
	v_fmac_f32_e32 v242, v244, v242
	v_mul_f32_e32 v244, v243, v242
	v_fma_f32 v245, -v241, v244, v243
	v_fmac_f32_e32 v244, v245, v242
	v_fma_f32 v241, -v241, v244, v243
	v_div_fmas_f32 v241, v241, v242, v244
	v_div_fixup_f32 v218, v241, v240, v218
	ds_write_b32 v28, v218 offset:34816
	s_waitcnt vmcnt(12)
	v_mul_f32_e32 v240, 0xbfb8aa3b, v219
	v_exp_f32_e32 v240, v240
	s_nop 0
	v_add_f32_e32 v240, 1.0, v240
	v_div_scale_f32 v241, s[18:19], v240, v240, v219
	v_rcp_f32_e32 v242, v241
	v_div_scale_f32 v243, vcc, v219, v240, v219
	v_fma_f32 v244, -v241, v242, 1.0
	v_fmac_f32_e32 v242, v244, v242
	v_mul_f32_e32 v244, v243, v242
	v_fma_f32 v245, -v241, v244, v243
	v_fmac_f32_e32 v244, v245, v242
	v_fma_f32 v241, -v241, v244, v243
	v_div_fmas_f32 v241, v241, v242, v244
	v_div_fixup_f32 v219, v241, v240, v219
	ds_write_b32 v28, v219 offset:35840
	s_waitcnt vmcnt(11)
	v_mul_f32_e32 v240, 0xbfb8aa3b, v220
	v_exp_f32_e32 v240, v240
	s_nop 0
	v_add_f32_e32 v240, 1.0, v240
	v_div_scale_f32 v241, s[18:19], v240, v240, v220
	v_rcp_f32_e32 v242, v241
	v_div_scale_f32 v243, vcc, v220, v240, v220
	v_fma_f32 v244, -v241, v242, 1.0
	v_fmac_f32_e32 v242, v244, v242
	v_mul_f32_e32 v244, v243, v242
	v_fma_f32 v245, -v241, v244, v243
	v_fmac_f32_e32 v244, v245, v242
	v_fma_f32 v241, -v241, v244, v243
	v_div_fmas_f32 v241, v241, v242, v244
	v_div_fixup_f32 v220, v241, v240, v220
	ds_write_b32 v28, v220 offset:36864
	s_waitcnt vmcnt(10)
	v_mul_f32_e32 v240, 0xbfb8aa3b, v221
	v_exp_f32_e32 v240, v240
	s_nop 0
	v_add_f32_e32 v240, 1.0, v240
	v_div_scale_f32 v241, s[18:19], v240, v240, v221
	v_rcp_f32_e32 v242, v241
	v_div_scale_f32 v243, vcc, v221, v240, v221
	v_fma_f32 v244, -v241, v242, 1.0
	v_fmac_f32_e32 v242, v244, v242
	v_mul_f32_e32 v244, v243, v242
	v_fma_f32 v245, -v241, v244, v243
	v_fmac_f32_e32 v244, v245, v242
	v_fma_f32 v241, -v241, v244, v243
	v_div_fmas_f32 v241, v241, v242, v244
	v_div_fixup_f32 v221, v241, v240, v221
	ds_write_b32 v28, v221 offset:37888
	s_waitcnt vmcnt(9)
; DEV float siluf_(float x) { return x / (1.0f + __expf(-x)); }
; DEV void mod_item(const Params& p, int item, unsigned char* smem) {
;     ...
;     for (int e = tid; e < 48 * 256; e += NT) {
;       int b = e >> 8, k = e & 255;
;       float c = b < 16 ? p.c_p[b * 1024 + kc * 256 + k] : p.c_s[(b - 16) * 1024 + kc * 256 + k];
;       sc[e] = siluf_(c);
;     }
	v_mul_f32_e32 v240, 0xbfb8aa3b, v222
	v_exp_f32_e32 v240, v240
	s_nop 0
	v_add_f32_e32 v240, 1.0, v240
	v_div_scale_f32 v241, s[18:19], v240, v240, v222
	v_rcp_f32_e32 v242, v241
	v_div_scale_f32 v243, vcc, v222, v240, v222
	v_fma_f32 v244, -v241, v242, 1.0
	v_fmac_f32_e32 v242, v244, v242
	v_mul_f32_e32 v244, v243, v242
	v_fma_f32 v245, -v241, v244, v243
	v_fmac_f32_e32 v244, v245, v242
	v_fma_f32 v241, -v241, v244, v243
	v_div_fmas_f32 v241, v241, v242, v244
	v_div_fixup_f32 v222, v241, v240, v222
	ds_write_b32 v28, v222 offset:38912
	s_waitcnt vmcnt(8)
	v_mul_f32_e32 v240, 0xbfb8aa3b, v223
	v_exp_f32_e32 v240, v240
	s_nop 0
	v_add_f32_e32 v240, 1.0, v240
	v_div_scale_f32 v241, s[18:19], v240, v240, v223
	v_rcp_f32_e32 v242, v241
	v_div_scale_f32 v243, vcc, v223, v240, v223
	v_fma_f32 v244, -v241, v242, 1.0
	v_fmac_f32_e32 v242, v244, v242
	v_mul_f32_e32 v244, v243, v242
	v_fma_f32 v245, -v241, v244, v243
	v_fmac_f32_e32 v244, v245, v242
	v_fma_f32 v241, -v241, v244, v243
	v_div_fmas_f32 v241, v241, v242, v244
	v_div_fixup_f32 v223, v241, v240, v223
	ds_write_b32 v28, v223 offset:39936
	s_waitcnt vmcnt(7)
	v_mul_f32_e32 v240, 0xbfb8aa3b, v224
	v_exp_f32_e32 v240, v240
	s_nop 0
	v_add_f32_e32 v240, 1.0, v240
	v_div_scale_f32 v241, s[18:19], v240, v240, v224
	v_rcp_f32_e32 v242, v241
	v_div_scale_f32 v243, vcc, v224, v240, v224
	v_fma_f32 v244, -v241, v242, 1.0
	v_fmac_f32_e32 v242, v244, v242
	v_mul_f32_e32 v244, v243, v242
	v_fma_f32 v245, -v241, v244, v243
	v_fmac_f32_e32 v244, v245, v242
	v_fma_f32 v241, -v241, v244, v243
	v_div_fmas_f32 v241, v241, v242, v244
	v_div_fixup_f32 v224, v241, v240, v224
	ds_write_b32 v28, v224 offset:40960
	s_waitcnt vmcnt(6)
	v_mul_f32_e32 v240, 0xbfb8aa3b, v225
	v_exp_f32_e32 v240, v240
	s_nop 0
	v_add_f32_e32 v240, 1.0, v240
	v_div_scale_f32 v241, s[18:19], v240, v240, v225
	v_rcp_f32_e32 v242, v241
	v_div_scale_f32 v243, vcc, v225, v240, v225
	v_fma_f32 v244, -v241, v242, 1.0
	v_fmac_f32_e32 v242, v244, v242
	v_mul_f32_e32 v244, v243, v242
	v_fma_f32 v245, -v241, v244, v243
	v_fmac_f32_e32 v244, v245, v242
	v_fma_f32 v241, -v241, v244, v243
	v_div_fmas_f32 v241, v241, v242, v244
	v_div_fixup_f32 v225, v241, v240, v225
	ds_write_b32 v28, v225 offset:41984
	s_waitcnt vmcnt(5)
	v_mul_f32_e32 v240, 0xbfb8aa3b, v226
	v_exp_f32_e32 v240, v240
	s_nop 0
	v_add_f32_e32 v240, 1.0, v240
	v_div_scale_f32 v241, s[18:19], v240, v240, v226
	v_rcp_f32_e32 v242, v241
	v_div_scale_f32 v243, vcc, v226, v240, v226
	v_fma_f32 v244, -v241, v242, 1.0
	v_fmac_f32_e32 v242, v244, v242
	v_mul_f32_e32 v244, v243, v242
	v_fma_f32 v245, -v241, v244, v243
	v_fmac_f32_e32 v244, v245, v242
	v_fma_f32 v241, -v241, v244, v243
	v_div_fmas_f32 v241, v241, v242, v244
	v_div_fixup_f32 v226, v241, v240, v226
	ds_write_b32 v28, v226 offset:43008
	s_waitcnt vmcnt(4)
	v_mul_f32_e32 v240, 0xbfb8aa3b, v227
	v_exp_f32_e32 v240, v240
	s_nop 0
	v_add_f32_e32 v240, 1.0, v240
	v_div_scale_f32 v241, s[18:19], v240, v240, v227
	v_rcp_f32_e32 v242, v241
	v_div_scale_f32 v243, vcc, v227, v240, v227
	v_fma_f32 v244, -v241, v242, 1.0
	v_fmac_f32_e32 v242, v244, v242
	v_mul_f32_e32 v244, v243, v242
	v_fma_f32 v245, -v241, v244, v243
	v_fmac_f32_e32 v244, v245, v242
	v_fma_f32 v241, -v241, v244, v243
	v_div_fmas_f32 v241, v241, v242, v244
	v_div_fixup_f32 v227, v241, v240, v227
	ds_write_b32 v28, v227 offset:44032
	s_waitcnt vmcnt(3)
	v_mul_f32_e32 v240, 0xbfb8aa3b, v228
	v_exp_f32_e32 v240, v240
	s_nop 0
	v_add_f32_e32 v240, 1.0, v240
	v_div_scale_f32 v241, s[18:19], v240, v240, v228
	v_rcp_f32_e32 v242, v241
	v_div_scale_f32 v243, vcc, v228, v240, v228
	v_fma_f32 v244, -v241, v242, 1.0
	v_fmac_f32_e32 v242, v244, v242
	v_mul_f32_e32 v244, v243, v242
	v_fma_f32 v245, -v241, v244, v243
	v_fmac_f32_e32 v244, v245, v242
	v_fma_f32 v241, -v241, v244, v243
	v_div_fmas_f32 v241, v241, v242, v244
	v_div_fixup_f32 v228, v241, v240, v228
	ds_write_b32 v28, v228 offset:45056
	s_waitcnt vmcnt(2)
	v_mul_f32_e32 v240, 0xbfb8aa3b, v229
	v_exp_f32_e32 v240, v240
	s_nop 0
	v_add_f32_e32 v240, 1.0, v240
	v_div_scale_f32 v241, s[18:19], v240, v240, v229
	v_rcp_f32_e32 v242, v241
	v_div_scale_f32 v243, vcc, v229, v240, v229
	v_fma_f32 v244, -v241, v242, 1.0
	v_fmac_f32_e32 v242, v244, v242
	v_mul_f32_e32 v244, v243, v242
	v_fma_f32 v245, -v241, v244, v243
	v_fmac_f32_e32 v244, v245, v242
	v_fma_f32 v241, -v241, v244, v243
	v_div_fmas_f32 v241, v241, v242, v244
	v_div_fixup_f32 v229, v241, v240, v229
	ds_write_b32 v28, v229 offset:46080
	s_waitcnt vmcnt(1)
	v_mul_f32_e32 v240, 0xbfb8aa3b, v230
	v_exp_f32_e32 v240, v240
	s_nop 0
	v_add_f32_e32 v240, 1.0, v240
	v_div_scale_f32 v241, s[18:19], v240, v240, v230
	v_rcp_f32_e32 v242, v241
	v_div_scale_f32 v243, vcc, v230, v240, v230
	v_fma_f32 v244, -v241, v242, 1.0
	v_fmac_f32_e32 v242, v244, v242
	v_mul_f32_e32 v244, v243, v242
	v_fma_f32 v245, -v241, v244, v243
	v_fmac_f32_e32 v244, v245, v242
	v_fma_f32 v241, -v241, v244, v243
	v_div_fmas_f32 v241, v241, v242, v244
	v_div_fixup_f32 v230, v241, v240, v230
	ds_write_b32 v28, v230 offset:47104
	s_waitcnt vmcnt(0)
	v_mul_f32_e32 v240, 0xbfb8aa3b, v231
	v_exp_f32_e32 v240, v240
	s_nop 0
	v_add_f32_e32 v240, 1.0, v240
	v_div_scale_f32 v241, s[18:19], v240, v240, v231
	v_rcp_f32_e32 v242, v241
	v_div_scale_f32 v243, vcc, v231, v240, v231
	v_fma_f32 v244, -v241, v242, 1.0
	v_fmac_f32_e32 v242, v244, v242
	v_mul_f32_e32 v244, v243, v242
	v_fma_f32 v245, -v241, v244, v243
	v_fmac_f32_e32 v244, v245, v242
	v_fma_f32 v241, -v241, v244, v243
	v_div_fmas_f32 v241, v241, v242, v244
	v_div_fixup_f32 v231, v241, v240, v231
	ds_write_b32 v28, v231 offset:48128
	s_branch .LBB0_194
